# mlstm_c: all 6 tile loads issued at item-loop top (were 5 serialized load-wait round trips), V transposition via ds_write_b16/d16_hi
# speedup vs baseline: 1.0035x; 1.0005x over previous
; __device__ __forceinline__ bf16_t f2bf(float f) { return (bf16_t)(cvt_pk_bf16(f, 0.f) & 0xffffu); }
; __device__ __forceinline__ float logsigmoidf_(float x) { return fminf(x, 0.f) - log1pf(__expf(-fabsf(x))); }
; __device__ __forceinline__ void phase_mlstm_c(const Args& a, unsigned char* lds) {
;     ...
;         const int c = item & 127, h = (item >> 7) & 3, b = item >> 9;
;         const size_t r0 = (size_t)b * SEQ + c * 64;
;         if (wave == 0) {
;             const float ig = SM[(r0 + lane) * 16 + 8 + h] + a.in[I_BI][h];
;             const float lf = logsigmoidf_(SM[(r0 + lane) * 16 + 12 + h] + a.in[I_BF][h]);
;             const float bs = wave_incl_sum(lf, lane);
;             const float av = ig - bs;
;             const float pm = wave_incl_max(av, lane);
;             const float m0 = MS[item];
;             const float mt = bs + fmaxf(pm, m0);
;             bS[lane] = bs; aS[lane] = av; mtS[lane] = mt; wiS[lane] = __expf(bs + m0 - mt);
;             nS[lane] = DN[item * 64 + lane];
;         }
;         { const int s = tid >> 3, d0 = (tid & 7) * 8;
;             *(u32x4*)(QS_ + s * 72 + d0) = *(const u32x4*)(QK + (r0 + s) * 512 + h * 64 + d0);
;             *(u32x4*)(KS + s * 72 + d0) = *(const u32x4*)(QK + (r0 + s) * 512 + 256 + h * 64 + d0); }
;         for (int i = tid; i < 1024; i += 512) { const int s = i >> 4, d0 = (i & 15) * 8; float f[8]; unpack8(*(const u32x4*)(P + (r0 + s) * LDP + C_MV + h * 128 + d0), f);
; #pragma unroll
;             for (int e = 0; e < 8; ++e) BT[(d0 + e) * 136 + s] = f2bf(f[e]); }
;         { const bf16_t* st = ST + (size_t)item * 8192;
;             for (int i = tid; i < 1024; i += 512) { const int dv = i >> 3, k0 = (i & 7) * 8; *(u32x4*)(BT + dv * 136 + 64 + k0) = *(const u32x4*)(st + dv * 64 + k0); } }
.LBB0_795:
	s_ashr_i32 s64, s62, 9
	s_ashr_i32 s65, s64, 31
	s_lshl_b32 s92, s62, 6
	s_lshl_b64 s[64:65], s[64:65], 13
	s_and_b32 s33, s92, 0x1fc0
	s_ashr_i32 s63, s62, 31
	s_bfe_u32 s91, s62, 0x20007
	s_or_b32 s66, s64, s33
	s_mov_b32 s67, s65
	v_lshl_add_u64 v[252:253], s[66:67], 0, v[128:129]
	v_lshlrev_b64 v[252:253], 10, v[252:253]
	v_lshl_add_u64 v[252:253], s[0:1], 0, v[252:253]
	s_lshl_b32 s38, s91, 7
	v_lshl_add_u64 v[252:253], v[252:253], 0, s[38:39]
	v_mov_b32_e32 v251, v5
	v_mov_b32_e32 v250, v12
	v_lshl_add_u64 v[252:253], v[252:253], 0, v[250:251]
	global_load_dwordx4 v[228:231], v[252:253], off
	global_load_dwordx4 v[232:235], v[252:253], off offset:512
	s_lshr_b32 s33, s62, 7
	s_and_b32 s38, s81, 0x1fc0
	s_and_b32 s33, s33, 3
	s_add_u32 s64, s38, s64
	s_addc_u32 s65, 0, s65
	v_lshl_add_u64 v[252:253], s[64:65], 0, v[16:17]
	v_mad_u64_u32 v[250:251], vcc, v252, s88, 0
	v_mad_i32_i24 v253, v253, s88, v251
	v_lshl_or_b32 v252, s33, 8, v250
	v_lshl_add_u64 v[252:253], v[8:9], 0, v[252:253]
	s_lshl_b64 s[94:95], s[62:63], 14
	global_load_dwordx4 v[236:239], v[252:253], off
	s_nop 0
	v_lshl_add_u64 v[252:253], v[252:253], 0, s[40:41]
	global_load_dwordx4 v[240:243], v[252:253], off
	s_nop 0
	v_lshl_add_u64 v[252:253], v[10:11], 0, s[94:95]
	global_load_dwordx4 v[244:247], v[252:253], off
	s_nop 0
	v_lshl_add_u64 v[252:253], v[252:253], 0, s[42:43]
	global_load_dwordx4 v[248:251], v[252:253], off
	s_and_saveexec_b64 s[76:77], s[4:5]
	s_cbranch_execz .LBB0_797
	v_mov_b32_e32 v1, s67
	v_or_b32_e32 v0, s66, v156
	v_lshlrev_b64 v[0:1], 6, v[0:1]
	v_lshl_add_u64 v[0:1], s[58:59], 0, v[0:1]
	s_lshl_b32 s38, s91, 2
	v_lshl_add_u64 v[0:1], v[0:1], 0, s[38:39]
	v_mov_b32_e32 v2, s38
	global_load_dword v3, v[0:1], off offset:48
	global_load_dword v4, v2, s[50:51]
	s_nop 0
	global_load_dword v2, v2, s[48:49]
	s_nop 0
	global_load_dword v13, v[0:1], off offset:32
	s_lshl_b64 s[94:95], s[62:63], 2
	v_or_b32_e32 v0, s92, v156
	s_add_u32 s92, s78, s94
	v_ashrrev_i32_e32 v1, 31, v0
	s_addc_u32 s93, s79, s95
	v_lshl_add_u64 v[0:1], v[0:1], 2, s[36:37]
	global_load_dword v77, v5, s[92:93]
	global_load_dword v78, v[0:1], off
	v_mov_b32_e32 v14, v5
	v_mov_b32_e32 v15, v5
	v_mov_b32_e32 v71, 0xff800000
	v_mov_b32_e32 v72, 0xff800000
	v_mov_b32_e32 v73, 0xff800000
	v_mov_b32_e32 v74, 0xff800000
	v_mov_b32_e32 v75, 0xff800000
	v_mov_b32_e32 v76, 0xff800000
	s_waitcnt vmcnt(4)
	v_add_f32_e32 v3, v3, v4
	v_mul_f32_e64 v4, |v3|, s83
	v_exp_f32_e32 v4, v4
	s_waitcnt vmcnt(2)
	v_add_f32_e32 v2, v13, v2
	v_min_f32_e32 v3, 0, v3
	v_add_f32_e32 v13, 1.0, v4
	v_add_f32_e32 v79, -1.0, v13
	v_frexp_mant_f32_e32 v80, v13
	v_cvt_f64_f32_e32 v[0:1], v13
	v_sub_f32_e32 v81, v79, v13
	v_frexp_exp_i32_f64_e32 v0, v[0:1]
	v_cmp_gt_f32_e32 vcc, s84, v80
	v_sub_f32_e32 v79, v4, v79
	v_add_f32_e32 v1, 1.0, v81
	v_subbrev_co_u32_e32 v0, vcc, 0, v0, vcc
	v_add_f32_e32 v1, v79, v1
	v_sub_u32_e32 v79, 0, v0
	v_cvt_f32_i32_e32 v0, v0
	v_ldexp_f32 v13, v13, v79
	v_ldexp_f32 v1, v1, v79
	v_add_f32_e32 v79, -1.0, v13
	v_add_f32_e32 v80, 1.0, v13
	v_add_f32_e32 v81, 1.0, v79
	v_add_f32_e32 v82, -1.0, v80
	v_sub_f32_e32 v81, v13, v81
	v_sub_f32_e32 v13, v13, v82
	v_mul_f32_e32 v82, 0x3f317218, v0
	v_add_f32_e32 v81, v1, v81
	v_add_f32_e32 v1, v1, v13
	v_fma_f32 v13, v0, s85, -v82
	v_add_f32_e32 v83, v79, v81
	v_add_f32_e32 v84, v80, v1
	v_fmac_f32_e32 v13, 0xb102e308, v0
	v_sub_f32_e32 v0, v83, v79
	v_sub_f32_e32 v79, v84, v80
	v_rcp_f32_e32 v80, v84
	v_add_f32_e32 v85, v82, v13
	v_sub_f32_e32 v1, v1, v79
	v_sub_f32_e32 v79, v85, v82
	v_sub_f32_e32 v13, v13, v79
	v_mul_f32_e32 v79, v83, v80
	v_sub_f32_e32 v0, v81, v0
	v_mul_f32_e32 v81, v84, v79
	v_fma_f32 v82, v79, v84, -v81
	v_fmac_f32_e32 v82, v79, v1
	v_add_f32_e32 v86, v81, v82
	v_sub_f32_e32 v87, v83, v86
	v_sub_f32_e32 v81, v86, v81
	v_sub_f32_e32 v83, v83, v87
	v_sub_f32_e32 v81, v81, v82
	v_sub_f32_e32 v82, v83, v86
	v_add_f32_e32 v0, v0, v82
	v_add_f32_e32 v0, v81, v0
	v_add_f32_e32 v81, v87, v0
	v_mul_f32_e32 v82, v80, v81
	v_sub_f32_e32 v83, v87, v81
	v_mul_f32_e32 v86, v84, v82
	v_add_f32_e32 v0, v0, v83
	v_add_f32_e32 v83, v79, v82
	v_fma_f32 v84, v82, v84, -v86
	v_sub_f32_e32 v79, v83, v79
	v_fmac_f32_e32 v84, v82, v1
	v_sub_f32_e32 v1, v82, v79
	v_add_f32_e32 v79, v86, v84
	v_sub_f32_e32 v82, v79, v86
	v_sub_f32_e32 v86, v81, v79
	v_sub_f32_e32 v81, v81, v86
	v_sub_f32_e32 v79, v81, v79
	v_sub_f32_e32 v82, v82, v84
	v_add_f32_e32 v0, v0, v79
	v_add_f32_e32 v0, v82, v0
	v_add_f32_e32 v0, v86, v0
	v_mul_f32_e32 v0, v80, v0
	v_add_f32_e32 v0, v1, v0
	v_add_f32_e32 v1, v83, v0
	v_mul_f32_e32 v79, v1, v1
	v_fmamk_f32 v82, v79, 0x3e9b6dac, v61
	v_sub_f32_e32 v80, v1, v83
	v_ldexp_f32 v81, v1, 1
	v_mul_f32_e32 v1, v1, v79
	v_fmaak_f32 v79, v79, v82, 0x3f2aaada
	v_mul_f32_e32 v1, v1, v79
	v_add_f32_e32 v79, v81, v1
	v_sub_f32_e32 v0, v0, v80
	v_sub_f32_e32 v80, v79, v81
	v_ldexp_f32 v0, v0, 1
	v_sub_f32_e32 v1, v1, v80
	v_add_f32_e32 v0, v0, v1
	v_add_f32_e32 v1, v79, v0
	v_sub_f32_e32 v79, v1, v79
	v_add_f32_e32 v80, v85, v1
	v_sub_f32_e32 v0, v0, v79
	v_sub_f32_e32 v79, v80, v85
	v_sub_f32_e32 v81, v80, v79
	v_sub_f32_e32 v1, v1, v79
	v_add_f32_e32 v79, v13, v0
	v_sub_f32_e32 v81, v85, v81
	v_sub_f32_e32 v82, v79, v13
	v_add_f32_e32 v1, v1, v81
	v_sub_f32_e32 v81, v79, v82
	v_sub_f32_e32 v0, v0, v82
	v_sub_f32_e32 v13, v13, v81
	v_add_f32_e32 v1, v79, v1
	v_add_f32_e32 v0, v0, v13
	v_add_f32_e32 v13, v80, v1
	v_sub_f32_e32 v79, v13, v80
	v_sub_f32_e32 v1, v1, v79
	v_add_f32_e32 v0, v0, v1
	v_add_f32_e32 v0, v13, v0
	v_cmp_neq_f32_e32 vcc, s86, v4
	s_nop 1
	v_cndmask_b32_e32 v0, v65, v0, vcc
	v_cmp_ngt_f32_e32 vcc, -1.0, v4
	s_nop 1
	v_cndmask_b32_e32 v0, v66, v0, vcc
	v_cmp_neq_f32_e32 vcc, -1.0, v4
	s_nop 1
	v_cndmask_b32_e32 v0, v62, v0, vcc
	v_cmp_lt_f32_e64 vcc, |v4|, s87
	s_nop 1
	v_cndmask_b32_e32 v0, v0, v4, vcc
	v_sub_f32_e32 v0, v3, v0
	s_nop 1
	v_add_f32_dpp v0, v0, v0 row_shr:1 row_mask:0xf bank_mask:0xf bound_ctrl:1
	s_nop 1
	v_add_f32_dpp v0, v0, v0 row_shr:2 row_mask:0xf bank_mask:0xf bound_ctrl:1
	s_nop 1
	v_add_f32_dpp v0, v0, v0 row_shr:4 row_mask:0xf bank_mask:0xf bound_ctrl:1
	s_nop 1
	v_add_f32_dpp v0, v0, v0 row_shr:8 row_mask:0xf bank_mask:0xf bound_ctrl:1
	s_nop 1
	v_mov_b32_dpp v14, v0 row_bcast:15 row_mask:0xa bank_mask:0xf
	v_add_f32_e32 v0, v0, v14
	s_nop 1
	v_mov_b32_dpp v15, v0 row_bcast:31 row_mask:0xc bank_mask:0xf
	v_add_f32_e32 v0, v0, v15
	v_sub_f32_e32 v1, v2, v0
	s_waitcnt vmcnt(1)
; __device__ __forceinline__ bf16_t f2bf(float f) { return (bf16_t)(cvt_pk_bf16(f, 0.f) & 0xffffu); }
; __device__ __forceinline__ void phase_mlstm_c(const Args& a, unsigned char* lds) {
;     ...
;             const float pm = wave_incl_max(av, lane);
;             const float m0 = MS[item];
;             const float mt = bs + fmaxf(pm, m0);
;             bS[lane] = bs; aS[lane] = av; mtS[lane] = mt; wiS[lane] = __expf(bs + m0 - mt);
;             nS[lane] = DN[item * 64 + lane];
;         }
;         { const int s = tid >> 3, d0 = (tid & 7) * 8;
;             *(u32x4*)(QS_ + s * 72 + d0) = *(const u32x4*)(QK + (r0 + s) * 512 + h * 64 + d0);
;             *(u32x4*)(KS + s * 72 + d0) = *(const u32x4*)(QK + (r0 + s) * 512 + 256 + h * 64 + d0); }
;         for (int i = tid; i < 1024; i += 512) { const int s = i >> 4, d0 = (i & 15) * 8; float f[8]; unpack8(*(const u32x4*)(P + (r0 + s) * LDP + C_MV + h * 128 + d0), f);
; #pragma unroll
;             for (int e = 0; e < 8; ++e) BT[(d0 + e) * 136 + s] = f2bf(f[e]); }
;         { const bf16_t* st = ST + (size_t)item * 8192;
;             for (int i = tid; i < 1024; i += 512) { const int dv = i >> 3, k0 = (i & 7) * 8; *(u32x4*)(BT + dv * 136 + 64 + k0) = *(const u32x4*)(st + dv * 64 + k0); } }
;         __syncthreads();
	v_add_f32_e32 v2, v77, v0
	v_mov_b32_dpp v71, v1 row_shr:1 row_mask:0xf bank_mask:0xf
	v_max_f32_e32 v3, v71, v71
	v_max_f32_e32 v3, v1, v3
	s_nop 1
	v_mov_b32_dpp v72, v3 row_shr:2 row_mask:0xf bank_mask:0xf
	v_max_f32_e32 v4, v72, v72
	v_max_f32_e32 v3, v3, v4
	s_nop 1
	v_mov_b32_dpp v73, v3 row_shr:4 row_mask:0xf bank_mask:0xf
	v_max_f32_e32 v4, v73, v73
	v_max_f32_e32 v3, v3, v4
	s_nop 1
	v_mov_b32_dpp v74, v3 row_shr:8 row_mask:0xf bank_mask:0xf
	v_max_f32_e32 v4, v74, v74
	v_max_f32_e32 v3, v3, v4
	s_nop 1
	v_mov_b32_dpp v75, v3 row_bcast:15 row_mask:0xa bank_mask:0xf
	v_max_f32_e32 v4, v75, v75
	v_max_f32_e32 v3, v3, v4
	s_nop 1
	v_mov_b32_dpp v76, v3 row_bcast:31 row_mask:0xc bank_mask:0xf
	v_max3_f32 v3, v3, v76, v77
	v_add_f32_e32 v3, v0, v3
	v_sub_f32_e32 v2, v2, v3
	v_mul_f32_e32 v2, 0x3fb8aa3b, v2
	v_exp_f32_e32 v2, v2
	ds_write_b32 v7, v0
	ds_write_b32 v18, v1
	ds_write_b32 v19, v3
	ds_write_b32 v20, v2
	s_waitcnt vmcnt(0)
	ds_write_b32 v21, v78
.LBB0_797:
	s_or_b64 exec, exec, s[76:77]
	v_lshl_add_u64 v[14:15], s[66:67], 0, v[128:129]
	v_and_b32_e32 v13, 0x78, v162
	v_mad_u32_u24 v13, v13, s80, v60
	s_waitcnt vmcnt(5)
	ds_write_b128 v22, v[228:231]
	s_waitcnt vmcnt(4)
	ds_write_b128 v22, v[232:235] offset:9216
	s_waitcnt vmcnt(3)
	ds_write_b16 v13, v236
	ds_write_b16_d16_hi v13, v236 offset:272
	ds_write_b16 v13, v237 offset:544
	ds_write_b16_d16_hi v13, v237 offset:816
	ds_write_b16 v13, v238 offset:1088
	ds_write_b16_d16_hi v13, v238 offset:1360
	ds_write_b16 v13, v239 offset:1632
	ds_write_b16_d16_hi v13, v239 offset:1904
	s_waitcnt vmcnt(2)
	ds_write_b16 v13, v240 offset:64
	ds_write_b16_d16_hi v13, v240 offset:336
	ds_write_b16 v13, v241 offset:608
	ds_write_b16_d16_hi v13, v241 offset:880
	ds_write_b16 v13, v242 offset:1152
	ds_write_b16_d16_hi v13, v242 offset:1424
	ds_write_b16 v13, v243 offset:1696
	ds_write_b16_d16_hi v13, v243 offset:1968
	s_waitcnt vmcnt(1)
	ds_write_b128 v32, v[244:247]
	s_waitcnt vmcnt(0)
	ds_write_b128 v32, v[248:251] offset:17408
	v_mov_b32_e32 v4, 0
	v_mov_b32_e32 v0, 0
	v_mov_b32_e32 v1, 0
	v_mov_b32_e32 v2, 0
	v_mov_b32_e32 v3, 0
	s_waitcnt lgkmcnt(0)
	s_barrier
	s_and_saveexec_b64 s[64:65], s[8:9]
	s_cbranch_execz .LBB0_803
	ds_read_b128 v[0:3], v23
	ds_read_b128 v[72:75], v23 offset:64
	ds_read_b128 v[76:79], v67 offset:9216
	ds_read_b128 v[80:83], v67 offset:9280
	s_waitcnt lgkmcnt(1)
	v_mfma_f32_16x16x32_bf16 v[0:3], v[0:3], v[76:79], 0
	s_waitcnt lgkmcnt(0)
	v_mfma_f32_16x16x32_bf16 v[0:3], v[72:75], v[80:83], v[0:3]
